# static helper priority: waves 4-7 keep s_setprio 3 for the whole chain (no per-chunk reset), reset only at the chain's last chunk
# baseline (speedup 1.0000x reference)
.Lmy_ck_drE_h:
	s_waitcnt lgkmcnt(0)
	s_bfe_u32 s96, s62, 0x20006
	s_and_b32 s97, s96, 1
	s_mul_i32 s97, s97, 0x2700
	s_mov_b32 s101, 0x1c000
	s_mov_b32 s100, 0x6100
	s_bitcmp0_b32 s65, 0
	s_cselect_b32 s101, 0xe000, s101
	s_cselect_b32 s100, 0x4e00, s100
	s_cmp_gt_u32 s96, 1
	s_cselect_b32 s100, s100, 0
	s_add_i32 s97, s97, s101
	s_add_i32 s97, s97, s100
	s_mov_b32 s96, s97
	v_and_b32_e32 v72, 3, v233
	v_lshrrev_b32_e32 v73, 2, v233
	v_lshlrev_b32_e32 v72, 2, v72
	v_lshl_add_u32 v72, v73, 8, v72
	v_lshl_add_u32 v72, v234, 6, v72
	s_add_i32 s97, s96, 0x1000
	v_add_u32_e32 v78, s97, v72
	v_xor_b32_e32 v79, v224, v234
	v_lshl_add_u32 v79, v79, 4, s96
	ds_read_b128 v[96:99], v79
	ds_read_b128 v[100:103], v79 offset:1024
	ds_read_b128 v[104:107], v79 offset:2048
	ds_read_b128 v[108:111], v79 offset:3072
	ds_read_b32 v80, v78
	ds_read_b32 v81, v78 offset:16
	ds_read_b32 v82, v78 offset:32
	ds_read_b32 v83, v78 offset:48
	ds_read_b32 v84, v78 offset:1024
	ds_read_b32 v85, v78 offset:1040
	ds_read_b32 v86, v78 offset:1056
	ds_read_b32 v87, v78 offset:1072
	ds_read_b32 v88, v78 offset:2048
	ds_read_b32 v89, v78 offset:2064
	ds_read_b32 v90, v78 offset:2080
	ds_read_b32 v91, v78 offset:2096
	ds_read_b32 v92, v78 offset:3072
	ds_read_b32 v93, v78 offset:3088
	ds_read_b32 v94, v78 offset:3104
	ds_read_b32 v95, v78 offset:3120
	v_lshl_add_u32 v74, v224, 2, s96
	ds_write_b32 v74, v235 offset:9728
	v_add_u32_e32 v75, -1, v233
	v_mov_b32_e32 v76, -1
	v_cndmask_b32_e64 v75, v76, v75, s[98:99]
	v_cmp_lt_u32_e64 s[100:101], 7, v233
	v_add_u32_e32 v76, -8, v233
	v_and_b32_e32 v77, 1, v234
	v_cndmask_b32_e64 v75, v75, v76, s[100:101]
	v_lshlrev_b32_e32 v77, 2, v77
	v_sub_u32_e32 v76, v75, v77
	v_lshlrev_b32_e32 v77, 2, v234
	v_sub_u32_e32 v77, v233, v77
	v_add_u32_e32 v77, -1, v77
	s_waitcnt lgkmcnt(15)
	v_mfma_f32_16x16x4_f32 v[244:247], v80, v96, 0
	v_mfma_f32_16x16x4_f32 v[240:243], v81, v97, 0
	s_waitcnt lgkmcnt(14)
	v_mfma_f32_16x16x4_f32 v[244:247], v82, v98, v[244:247]
	s_waitcnt lgkmcnt(13)
	v_mfma_f32_16x16x4_f32 v[240:243], v83, v99, v[240:243]
	s_waitcnt lgkmcnt(12)
	v_mfma_f32_16x16x4_f32 v[244:247], v84, v100, v[244:247]
	s_waitcnt lgkmcnt(11)
	v_mfma_f32_16x16x4_f32 v[240:243], v85, v101, v[240:243]
	s_waitcnt lgkmcnt(10)
	v_mfma_f32_16x16x4_f32 v[244:247], v86, v102, v[244:247]
	s_waitcnt lgkmcnt(9)
	v_mfma_f32_16x16x4_f32 v[240:243], v87, v103, v[240:243]
	s_waitcnt lgkmcnt(8)
	v_mfma_f32_16x16x4_f32 v[244:247], v88, v104, v[244:247]
	s_waitcnt lgkmcnt(7)
	v_mfma_f32_16x16x4_f32 v[240:243], v89, v105, v[240:243]
	s_waitcnt lgkmcnt(6)
	v_mfma_f32_16x16x4_f32 v[244:247], v90, v106, v[244:247]
	s_waitcnt lgkmcnt(5)
	v_mfma_f32_16x16x4_f32 v[240:243], v91, v107, v[240:243]
	s_waitcnt lgkmcnt(4)
	v_mfma_f32_16x16x4_f32 v[244:247], v92, v108, v[244:247]
	s_waitcnt lgkmcnt(3)
	v_mfma_f32_16x16x4_f32 v[240:243], v93, v109, v[240:243]
	s_waitcnt lgkmcnt(2)
	v_mfma_f32_16x16x4_f32 v[244:247], v94, v110, v[244:247]
	s_waitcnt lgkmcnt(1)
	v_mfma_f32_16x16x4_f32 v[240:243], v95, v111, v[240:243]
	s_nop 9
	v_add_f32_e32 v244, v244, v240
	v_add_f32_e32 v245, v245, v241
	v_add_f32_e32 v246, v246, v242
	v_add_f32_e32 v247, v247, v243
	v_cmp_le_i32_e64 s[96:97], 0, v76
	v_cmp_le_i32_e64 s[100:101], 1, v76
	s_nop 0
	v_cndmask_b32_e64 v128, 0, v244, s[96:97]
	v_cndmask_b32_e64 v129, 0, v245, s[100:101]
	v_cmp_le_i32_e64 s[96:97], 2, v76
	v_cmp_le_i32_e64 s[100:101], 3, v76
	s_nop 0
	v_cndmask_b32_e64 v130, 0, v246, s[96:97]
	v_cndmask_b32_e64 v131, 0, v247, s[100:101]
	s_bfe_u32 s96, s62, 0x20006
	s_and_b32 s97, s96, 1
	s_mul_i32 s97, s97, 0x2700
	s_mov_b32 s101, 0x1c000
	s_mov_b32 s100, 0x6100
	s_bitcmp0_b32 s65, 0
	s_cselect_b32 s101, 0xe000, s101
	s_cselect_b32 s100, 0x4e00, s100
	s_cmp_gt_u32 s96, 1
	s_cselect_b32 s100, s100, 0
	s_add_i32 s97, s97, s101
	s_add_i32 s97, s97, s100
	v_xor_b32_e32 v74, v224, v234
	v_lshl_add_u32 v74, v74, 4, s97
	ds_write_b128 v74, v[128:131] offset:8448
	v_lshlrev_b32_e32 v75, 7, v234
	v_lshl_add_u32 v75, v233, 2, v75
	v_add_u32_e32 v75, s97, v75
	v_cmp_le_i32_e64 s[96:97], 0, v77
	v_cmp_le_i32_e64 s[100:101], 1, v77
	s_nop 0
	v_cndmask_b32_e64 v132, 0, v244, s[96:97]
	v_cndmask_b32_e64 v133, 0, v245, s[100:101]
	v_cmp_le_i32_e64 s[96:97], 2, v77
	v_cmp_le_i32_e64 s[100:101], 3, v77
	s_nop 0
	v_cndmask_b32_e64 v134, 0, v246, s[96:97]
	v_cndmask_b32_e64 v135, 0, v247, s[100:101]
	s_mov_b64 exec, 0x00ff00ff
	ds_write_b32 v75, v132 offset:9472
	ds_write_b32 v75, v133 offset:9504
	ds_write_b32 v75, v134 offset:9536
	ds_write_b32 v75, v135 offset:9568
	s_mov_b64 exec, -1
	s_branch .LBB0_655
	s_nop 0
	s_nop 0
	s_nop 0
	s_nop 0
	s_nop 0
	s_nop 0
	s_nop 0
	s_nop 0
	s_nop 0
	s_nop 0
	s_nop 0
	s_nop 0
	s_nop 0
	s_nop 0
	s_nop 0
	s_nop 0
	s_nop 0
	s_nop 0
	s_nop 0
	s_nop 0
	s_nop 0
	s_nop 0
	s_nop 0
	s_nop 0
	s_nop 0
	s_nop 0
	s_nop 0
	s_nop 0
	s_nop 0
	s_nop 0
	s_nop 0
	s_nop 0
	s_nop 0
	s_nop 0
	s_nop 0
	s_nop 0
	s_nop 0
	s_nop 0
	s_nop 0
	s_nop 0
	s_nop 0
	s_nop 0
	s_nop 0
